# P2|P3 team barrier: own and previous-panel counters polled with two loads issued together (were two dependent round trips)
# baseline (speedup 1.0000x reference)
.LBB0_366:
	s_or_b64 exec, exec, s[20:21]
	s_and_b32 s0, s1, 7
	s_add_u32 s1, s6, 0xffffff00
	s_addc_u32 s10, s7, -1
	s_cmp_lg_u32 s0, 0
	s_cselect_b32 s11, s10, 0
	s_cselect_b32 s10, s1, 0
	s_cmp_lg_u64 s[10:11], 0
	s_mov_b32 s0, 1
	s_cselect_b64 s[20:21], -1, 0
	s_cselect_b32 s96, s10, s6
	s_cselect_b32 s97, s11, s7
	v_mov_b32_e32 v2, 0
	s_branch .LBB0_368

.LBB0_368:
	global_load_dword v3, v2, s[6:7] sc1
	global_load_dword v6, v2, s[96:97] sc1
	s_mov_b64 s[26:27], -1
	s_waitcnt vmcnt(0)
	v_min_u32_e32 v3, v3, v6
	v_cmp_gt_u32_e64 s[28:29], 8, v3
